# tile boundary: header drain removed on the loop-back path, first two waits of the peeled trip widened by the epilogue's trailing store count (P4 P5 P6) so the store drain overlaps the next K-loop
# speedup vs baseline: 1.0010x; 1.0010x over previous
.LBB0_460:
	v_readlane_b32 s72, v249, 0
	v_readlane_b32 s84, v249, 12
	v_readlane_b32 s85, v249, 13
	v_readlane_b32 s86, v249, 14
	v_readlane_b32 s87, v249, 15
	s_mov_b64 s[28:29], s[84:85]
	s_mov_b64 s[30:31], s[86:87]
	s_add_u32 s20, s30, 0x4900000
	s_addc_u32 s21, s31, 0
	s_add_u32 s22, s30, 0x50000
	s_addc_u32 s23, s31, 0
	s_lshl_b32 s1, s1, 5
	s_mov_b64 s[24:25], 0x80
	s_and_b32 s42, s1, 0x60
	s_add_i32 m0, s56, 0x18000
	v_lshl_add_u64 v[4:5], v[4:5], 0, s[24:25]
	s_lshl_b32 s5, s0, 13
	s_lshl_b32 s1, s42, 7
	s_waitcnt vmcnt(2)
	s_barrier
	global_load_lds_dwordx4 v[4:5], off
	v_lshl_add_u64 v[4:5], v[6:7], 0, s[24:25]
	s_add_i32 m0, s56, 0x1a000
	s_add_i32 s61, s56, 0x8000
	s_add_i32 s62, s56, 0xa000
	global_load_lds_dwordx4 v[4:5], off
	v_lshl_add_u64 v[0:1], v[0:1], 0, s[24:25]
	s_mov_b32 m0, s61
	s_mov_b64 s[36:37], 0x20080
	s_add_u32 s38, s52, 0x40080
	global_load_lds_dwordx4 v[0:1], off
	v_lshl_add_u64 v[0:1], v[2:3], 0, s[36:37]
	s_mov_b32 m0, s62
	s_addc_u32 s39, s53, 0
	global_load_lds_dwordx4 v[0:1], off
	s_add_i32 m0, s56, 0x1c000
	v_lshl_add_u64 v[0:1], s[38:39], 0, v[130:131]
	global_load_lds_dwordx4 v[0:1], off
	v_lshl_add_u64 v[0:1], s[38:39], 0, v[134:135]
	s_add_i32 m0, s56, 0x1e000
	v_lshlrev_b32_e32 v3, 2, v219
	global_load_lds_dwordx4 v[0:1], off
	v_bfe_u32 v0, v219, 4, 2
	v_and_b32_e32 v1, 15, v219
	v_lshlrev_b32_e32 v2, 4, v0
	v_lshl_or_b32 v148, s0, 6, v1
	v_lshl_or_b32 v1, v1, 6, v2
	v_and_b32_e32 v3, 32, v3
	v_bitop3_b32 v4, v1, s5, v3 bitop3:0xde
	v_lshlrev_b32_e32 v1, 6, v219
	s_movk_i32 s0, 0x3c0
	v_and_or_b32 v1, v1, s0, v2
	v_bitop3_b32 v149, s1, v1, v3 bitop3:0xf6
	v_cmp_eq_u32_e64 s[0:1], 0, v0
	v_lshl_or_b32 v150, v0, 3, s42
	v_lshlrev_b32_e32 v0, 8, v219
	v_and_b32_e32 v0, 0x18000, v0
	v_lshlrev_b32_e32 v2, 11, v10
	v_or3_b32 v0, v8, v0, v2
	s_mov_b64 s[40:41], 0x40080
	v_add_u32_e32 v0, v0, v9
	v_mov_b32_e32 v1, v131
	v_lshl_add_u64 v[136:137], v[0:1], 0, s[40:41]
	v_lshlrev_b32_e32 v0, 4, v11
	v_and_b32_e32 v0, 0x18000, v0
	v_readlane_b32 s80, v249, 8
	v_readlane_b32 s81, v249, 9
	v_readlane_b32 s82, v249, 10
	v_readlane_b32 s83, v249, 11
	v_or3_b32 v0, v8, v0, v2
	s_waitcnt vmcnt(6)
	s_cmpk_lt_u32 s4, 0x100
	s_mov_b64 s[80:81], s[88:89]
	v_add_u32_e32 v0, v0, v9
	s_mov_b64 s[4:5], 0x60080
	s_cselect_b64 s[38:39], -1, 0
	s_mov_b64 s[82:83], s[90:91]
	v_lshl_add_u64 v[138:139], v[0:1], 0, s[4:5]
	s_add_i32 s67, 0, 0x10000
	s_add_i32 s72, 0, 0x14000
	v_mbcnt_lo_u32_b32 v0, -1, 0
	v_readlane_b32 s73, v249, 1
	s_ashr_i32 s63, s82, 31
	s_mov_b32 s64, s82
	s_ashr_i32 s65, s2, 31
	v_mov_b64_e32 v[140:141], 0x500
	v_mov_b64_e32 v[142:143], 0x4ff
	s_movk_i32 s66, 0xa1
	v_add_u32_e32 v151, s67, v149
	v_add_u32_e32 v152, s72, v149
	v_add_u32_e32 v153, 0, v4
	v_mbcnt_hi_u32_b32 v154, -1, v0
	v_readlane_b32 s74, v249, 2
	v_readlane_b32 s75, v249, 3
	v_readlane_b32 s76, v249, 4
	v_readlane_b32 s77, v249, 5
	v_readlane_b32 s78, v249, 6
	v_readlane_b32 s79, v249, 7
	s_barrier
	s_waitcnt vmcnt(0)
	s_branch .LBB0_463

.LBB0_465:
	s_lshl_b32 s42, s73, 8
	s_ashr_i32 s43, s42, 31
	s_lshl_b64 s[42:43], s[42:43], 11
	s_add_u32 s42, s10, s42
	s_addc_u32 s43, s11, s43
	s_and_b64 s[44:45], s[4:5], exec
	s_cselect_b32 s47, s43, s49
	s_cselect_b32 s74, s42, s48
	s_ashr_i32 s41, s40, 31
	s_lshl_b64 s[44:45], s[40:41], 19
	s_add_u32 s44, s33, s44
	s_addc_u32 s45, s34, s45
	s_and_b64 s[50:51], s[4:5], exec
	s_cselect_b32 s41, s45, s53
	s_cselect_b32 s50, s44, s52
	s_add_u32 s51, s52, 0x100
	s_addc_u32 s75, s53, 0
	s_mov_b32 s76, -2
	s_waitcnt lgkmcnt(0)
	s_waitcnt lgkmcnt(0)
	ds_read_b128 v[144:147], v151
	ds_read_b128 v[156:159], v151 offset:1024
	ds_read_b128 v[160:163], v151 offset:2048
	ds_read_b128 v[164:167], v151 offset:3072
	ds_read_b128 v[168:171], v152
	ds_read_b128 v[172:175], v152 offset:1024
	ds_read_b128 v[176:179], v152 offset:2048
	ds_read_b128 v[180:183], v152 offset:3072
	s_add_u32 s52, s48, 0x100
	s_addc_u32 s53, s49, 0
	s_cmp_eq_u32 s76, 12
	s_cselect_b32 s79, s47, s53
	s_cselect_b32 s78, s74, s52
	s_cselect_b32 s55, s41, s75
	s_cselect_b32 s54, s50, s51
	v_lshl_add_u64 v[216:217], s[48:49], 0, v[136:137]
	s_add_i32 m0, s56, 0xc000
	ds_read_b128 v[184:187], v153
	ds_read_b128 v[188:191], v153 offset:1024
	ds_read_b128 v[192:195], v153 offset:2048
	ds_read_b128 v[196:199], v153 offset:3072
	ds_read_b128 v[200:203], v153 offset:4096
	ds_read_b128 v[204:207], v153 offset:5120
	ds_read_b128 v[208:211], v153 offset:6144
	ds_read_b128 v[212:215], v153 offset:7168
	global_load_lds_dwordx4 v[216:217], off
	s_add_i32 m0, s56, 0xe000
	v_lshl_add_u64 v[216:217], s[48:49], 0, v[138:139]
	global_load_lds_dwordx4 v[216:217], off
	s_waitcnt vmcnt(24) lgkmcnt(0)
	s_setprio 1
	s_barrier
	v_mfma_f32_16x16x32_bf16 v[124:127], v[144:147], v[184:187], 0
	v_mfma_f32_16x16x32_bf16 v[120:123], v[160:163], v[184:187], 0
	v_mfma_f32_16x16x32_bf16 v[108:111], v[144:147], v[192:195], 0
	v_mfma_f32_16x16x32_bf16 v[104:107], v[160:163], v[192:195], 0
	v_mfma_f32_16x16x32_bf16 v[92:95], v[144:147], v[200:203], 0
	v_mfma_f32_16x16x32_bf16 v[88:91], v[160:163], v[200:203], 0
	v_mfma_f32_16x16x32_bf16 v[76:79], v[144:147], v[208:211], 0
	v_mfma_f32_16x16x32_bf16 v[72:75], v[160:163], v[208:211], 0
	v_mfma_f32_16x16x32_bf16 v[124:127], v[156:159], v[188:191], v[124:127]
	v_mfma_f32_16x16x32_bf16 v[120:123], v[164:167], v[188:191], v[120:123]
	v_mfma_f32_16x16x32_bf16 v[108:111], v[156:159], v[196:199], v[108:111]
	v_mfma_f32_16x16x32_bf16 v[104:107], v[164:167], v[196:199], v[104:107]
	v_mfma_f32_16x16x32_bf16 v[92:95], v[156:159], v[204:207], v[92:95]
	v_mfma_f32_16x16x32_bf16 v[88:91], v[164:167], v[204:207], v[88:91]
	v_mfma_f32_16x16x32_bf16 v[76:79], v[156:159], v[212:215], v[76:79]
	v_mfma_f32_16x16x32_bf16 v[72:75], v[164:167], v[212:215], v[72:75]
	v_mfma_f32_16x16x32_bf16 v[116:119], v[168:171], v[184:187], 0
	v_mfma_f32_16x16x32_bf16 v[112:115], v[176:179], v[184:187], 0
	v_mfma_f32_16x16x32_bf16 v[100:103], v[168:171], v[192:195], 0
	v_mfma_f32_16x16x32_bf16 v[96:99], v[176:179], v[192:195], 0
	v_mfma_f32_16x16x32_bf16 v[84:87], v[168:171], v[200:203], 0
	v_mfma_f32_16x16x32_bf16 v[80:83], v[176:179], v[200:203], 0
	v_mfma_f32_16x16x32_bf16 v[68:71], v[168:171], v[208:211], 0
	v_mfma_f32_16x16x32_bf16 v[64:67], v[176:179], v[208:211], 0
	v_mfma_f32_16x16x32_bf16 v[116:119], v[172:175], v[188:191], v[116:119]
	v_mfma_f32_16x16x32_bf16 v[112:115], v[180:183], v[188:191], v[112:115]
	v_mfma_f32_16x16x32_bf16 v[100:103], v[172:175], v[196:199], v[100:103]
	v_mfma_f32_16x16x32_bf16 v[96:99], v[180:183], v[196:199], v[96:99]
	v_mfma_f32_16x16x32_bf16 v[84:87], v[172:175], v[204:207], v[84:87]
	v_mfma_f32_16x16x32_bf16 v[80:83], v[180:183], v[204:207], v[80:83]
	v_mfma_f32_16x16x32_bf16 v[68:71], v[172:175], v[212:215], v[68:71]
	v_mfma_f32_16x16x32_bf16 v[64:67], v[180:183], v[212:215], v[64:67]
	s_barrier
	s_setprio 0
	s_add_i32 s48, s67, s35
	v_lshl_add_u64 v[216:217], s[54:55], 0, v[130:131]
	s_mov_b32 m0, s48
	ds_read_b128 v[184:187], v153 offset:16384
	ds_read_b128 v[188:191], v153 offset:17408
	ds_read_b128 v[192:195], v153 offset:18432
	ds_read_b128 v[196:199], v153 offset:19456
	ds_read_b128 v[200:203], v153 offset:20480
	ds_read_b128 v[204:207], v153 offset:21504
	ds_read_b128 v[208:211], v153 offset:22528
	ds_read_b128 v[212:215], v153 offset:23552
	global_load_lds_dwordx4 v[216:217], off
	s_add_i32 m0, s48, 0x2000
	s_add_u32 s48, s54, 0x40000
	v_lshl_add_u64 v[220:221], s[54:55], 0, v[134:135]
	s_addc_u32 s49, s55, 0
	s_add_i32 s68, s72, s35
	global_load_lds_dwordx4 v[220:221], off
	v_lshl_add_u64 v[224:225], s[48:49], 0, v[130:131]
	s_mov_b32 m0, s68
	v_lshl_add_u64 v[226:227], s[78:79], 0, v[132:133]
	global_load_lds_dwordx4 v[224:225], off
	v_lshl_add_u64 v[224:225], s[48:49], 0, v[134:135]
	s_add_i32 m0, s68, 0x2000
	v_lshl_add_u64 v[228:229], v[226:227], 0, s[12:13]
	global_load_lds_dwordx4 v[224:225], off
	s_mov_b32 m0, s56
	v_lshl_add_u64 v[224:225], s[78:79], 0, v[128:129]
	global_load_lds_dwordx4 v[224:225], off
	s_mov_b32 m0, s57
	s_nop 0
	global_load_lds_dwordx4 v[228:229], off
	s_waitcnt vmcnt(24) lgkmcnt(0)
	s_setprio 1
	s_barrier
	v_mfma_f32_16x16x32_bf16 v[60:63], v[144:147], v[184:187], 0
	v_mfma_f32_16x16x32_bf16 v[56:59], v[160:163], v[184:187], 0
	v_mfma_f32_16x16x32_bf16 v[44:47], v[144:147], v[192:195], 0
	v_mfma_f32_16x16x32_bf16 v[40:43], v[160:163], v[192:195], 0
	v_mfma_f32_16x16x32_bf16 v[28:31], v[144:147], v[200:203], 0
	v_mfma_f32_16x16x32_bf16 v[24:27], v[160:163], v[200:203], 0
	v_mfma_f32_16x16x32_bf16 v[12:15], v[144:147], v[208:211], 0
	v_mfma_f32_16x16x32_bf16 v[8:11], v[160:163], v[208:211], 0
	v_mfma_f32_16x16x32_bf16 v[60:63], v[156:159], v[188:191], v[60:63]
	v_mfma_f32_16x16x32_bf16 v[56:59], v[164:167], v[188:191], v[56:59]
	v_mfma_f32_16x16x32_bf16 v[44:47], v[156:159], v[196:199], v[44:47]
	v_mfma_f32_16x16x32_bf16 v[40:43], v[164:167], v[196:199], v[40:43]
	v_mfma_f32_16x16x32_bf16 v[28:31], v[156:159], v[204:207], v[28:31]
	v_mfma_f32_16x16x32_bf16 v[24:27], v[164:167], v[204:207], v[24:27]
	v_mfma_f32_16x16x32_bf16 v[12:15], v[156:159], v[212:215], v[12:15]
	v_mfma_f32_16x16x32_bf16 v[8:11], v[164:167], v[212:215], v[8:11]
	v_mfma_f32_16x16x32_bf16 v[52:55], v[168:171], v[184:187], 0
	v_mfma_f32_16x16x32_bf16 v[48:51], v[176:179], v[184:187], 0
	v_mfma_f32_16x16x32_bf16 v[36:39], v[168:171], v[192:195], 0
	v_mfma_f32_16x16x32_bf16 v[32:35], v[176:179], v[192:195], 0
	v_mfma_f32_16x16x32_bf16 v[20:23], v[168:171], v[200:203], 0
	v_mfma_f32_16x16x32_bf16 v[16:19], v[176:179], v[200:203], 0
	v_mfma_f32_16x16x32_bf16 v[4:7], v[168:171], v[208:211], 0
	v_mfma_f32_16x16x32_bf16 v[0:3], v[176:179], v[208:211], 0
	v_mfma_f32_16x16x32_bf16 v[52:55], v[172:175], v[188:191], v[52:55]
	v_mfma_f32_16x16x32_bf16 v[48:51], v[180:183], v[188:191], v[48:51]
	v_mfma_f32_16x16x32_bf16 v[36:39], v[172:175], v[196:199], v[36:39]
	v_mfma_f32_16x16x32_bf16 v[32:35], v[180:183], v[196:199], v[32:35]
	v_mfma_f32_16x16x32_bf16 v[20:23], v[172:175], v[204:207], v[20:23]
	v_mfma_f32_16x16x32_bf16 v[16:19], v[180:183], v[204:207], v[16:19]
	v_mfma_f32_16x16x32_bf16 v[4:7], v[172:175], v[212:215], v[4:7]
	v_mfma_f32_16x16x32_bf16 v[0:3], v[180:183], v[212:215], v[0:3]
	s_barrier
	s_setprio 0
	s_add_i32 s48, 0, 0x18000
	v_add_u32_e32 v155, s48, v149
	s_add_i32 s68, 0, 0x1c000
	ds_read_b128 v[144:147], v155
	ds_read_b128 v[156:159], v155 offset:1024
	ds_read_b128 v[160:163], v155 offset:2048
	ds_read_b128 v[164:167], v155 offset:3072
	v_add_u32_e32 v155, s68, v149
	ds_read_b128 v[168:171], v155
	ds_read_b128 v[172:175], v155 offset:1024
	ds_read_b128 v[176:179], v155 offset:2048
	ds_read_b128 v[180:183], v155 offset:3072
	s_mov_b32 m0, s58
	v_lshl_add_u64 v[228:229], v[224:225], 0, s[8:9]
	ds_read_b128 v[184:187], v153 offset:32768
	ds_read_b128 v[188:191], v153 offset:33792
	ds_read_b128 v[192:195], v153 offset:34816
	ds_read_b128 v[196:199], v153 offset:35840
	ds_read_b128 v[200:203], v153 offset:36864
	ds_read_b128 v[204:207], v153 offset:37888
	ds_read_b128 v[208:211], v153 offset:38912
	ds_read_b128 v[212:215], v153 offset:39936
	global_load_lds_dwordx4 v[228:229], off
	s_mov_b32 m0, s59
	v_lshl_add_u64 v[228:229], v[226:227], 0, s[14:15]
	global_load_lds_dwordx4 v[228:229], off
	s_waitcnt vmcnt(8) lgkmcnt(0)
	s_setprio 1
	s_barrier
	v_mfma_f32_16x16x32_bf16 v[124:127], v[144:147], v[184:187], v[124:127]
	v_mfma_f32_16x16x32_bf16 v[120:123], v[160:163], v[184:187], v[120:123]
	v_mfma_f32_16x16x32_bf16 v[108:111], v[144:147], v[192:195], v[108:111]
	v_mfma_f32_16x16x32_bf16 v[104:107], v[160:163], v[192:195], v[104:107]
	v_mfma_f32_16x16x32_bf16 v[92:95], v[144:147], v[200:203], v[92:95]
	v_mfma_f32_16x16x32_bf16 v[88:91], v[160:163], v[200:203], v[88:91]
	v_mfma_f32_16x16x32_bf16 v[76:79], v[144:147], v[208:211], v[76:79]
	v_mfma_f32_16x16x32_bf16 v[72:75], v[160:163], v[208:211], v[72:75]
	v_mfma_f32_16x16x32_bf16 v[124:127], v[156:159], v[188:191], v[124:127]
	v_mfma_f32_16x16x32_bf16 v[120:123], v[164:167], v[188:191], v[120:123]
	v_mfma_f32_16x16x32_bf16 v[108:111], v[156:159], v[196:199], v[108:111]
	v_mfma_f32_16x16x32_bf16 v[104:107], v[164:167], v[196:199], v[104:107]
	v_mfma_f32_16x16x32_bf16 v[92:95], v[156:159], v[204:207], v[92:95]
	v_mfma_f32_16x16x32_bf16 v[88:91], v[164:167], v[204:207], v[88:91]
	v_mfma_f32_16x16x32_bf16 v[76:79], v[156:159], v[212:215], v[76:79]
	v_mfma_f32_16x16x32_bf16 v[72:75], v[164:167], v[212:215], v[72:75]
	v_mfma_f32_16x16x32_bf16 v[116:119], v[168:171], v[184:187], v[116:119]
	v_mfma_f32_16x16x32_bf16 v[112:115], v[176:179], v[184:187], v[112:115]
	v_mfma_f32_16x16x32_bf16 v[100:103], v[168:171], v[192:195], v[100:103]
	v_mfma_f32_16x16x32_bf16 v[96:99], v[176:179], v[192:195], v[96:99]
	v_mfma_f32_16x16x32_bf16 v[84:87], v[168:171], v[200:203], v[84:87]
	v_mfma_f32_16x16x32_bf16 v[80:83], v[176:179], v[200:203], v[80:83]
	v_mfma_f32_16x16x32_bf16 v[68:71], v[168:171], v[208:211], v[68:71]
	v_mfma_f32_16x16x32_bf16 v[64:67], v[176:179], v[208:211], v[64:67]
	v_mfma_f32_16x16x32_bf16 v[116:119], v[172:175], v[188:191], v[116:119]
	v_mfma_f32_16x16x32_bf16 v[112:115], v[180:183], v[188:191], v[112:115]
	v_mfma_f32_16x16x32_bf16 v[100:103], v[172:175], v[196:199], v[100:103]
	v_mfma_f32_16x16x32_bf16 v[96:99], v[180:183], v[196:199], v[96:99]
	v_mfma_f32_16x16x32_bf16 v[84:87], v[172:175], v[204:207], v[84:87]
	v_mfma_f32_16x16x32_bf16 v[80:83], v[180:183], v[204:207], v[80:83]
	v_mfma_f32_16x16x32_bf16 v[68:71], v[172:175], v[212:215], v[68:71]
	v_mfma_f32_16x16x32_bf16 v[64:67], v[180:183], v[212:215], v[64:67]
	s_barrier
	s_setprio 0
	s_add_i32 s48, s48, s35
	v_lshl_add_u64 v[216:217], v[216:217], 0, s[24:25]
	s_mov_b32 m0, s48
	ds_read_b128 v[184:187], v153 offset:49152
	ds_read_b128 v[188:191], v153 offset:50176
	ds_read_b128 v[192:195], v153 offset:51200
	ds_read_b128 v[196:199], v153 offset:52224
	ds_read_b128 v[200:203], v153 offset:53248
	ds_read_b128 v[204:207], v153 offset:54272
	ds_read_b128 v[208:211], v153 offset:55296
	ds_read_b128 v[212:215], v153 offset:56320
	global_load_lds_dwordx4 v[216:217], off
	s_add_i32 m0, s48, 0x2000
	s_add_u32 s48, s54, 0x40080
	v_lshl_add_u64 v[216:217], v[220:221], 0, s[24:25]
	s_addc_u32 s49, s55, 0
	s_add_i32 s54, s68, s35
	global_load_lds_dwordx4 v[216:217], off
	s_mov_b32 m0, s54
	v_lshl_add_u64 v[216:217], s[48:49], 0, v[130:131]
	global_load_lds_dwordx4 v[216:217], off
	s_add_i32 m0, s54, 0x2000
	v_lshl_add_u64 v[216:217], s[48:49], 0, v[134:135]
	global_load_lds_dwordx4 v[216:217], off
	s_mov_b32 m0, s61
	v_lshl_add_u64 v[216:217], v[224:225], 0, s[24:25]
	global_load_lds_dwordx4 v[216:217], off
	s_mov_b32 m0, s62
	v_lshl_add_u64 v[216:217], v[226:227], 0, s[36:37]
	global_load_lds_dwordx4 v[216:217], off
	s_waitcnt vmcnt(8) lgkmcnt(0)
	s_setprio 1
	s_barrier
	v_mfma_f32_16x16x32_bf16 v[60:63], v[144:147], v[184:187], v[60:63]
	v_mfma_f32_16x16x32_bf16 v[56:59], v[160:163], v[184:187], v[56:59]
	v_mfma_f32_16x16x32_bf16 v[44:47], v[144:147], v[192:195], v[44:47]
	v_mfma_f32_16x16x32_bf16 v[40:43], v[160:163], v[192:195], v[40:43]
	v_mfma_f32_16x16x32_bf16 v[28:31], v[144:147], v[200:203], v[28:31]
	v_mfma_f32_16x16x32_bf16 v[24:27], v[160:163], v[200:203], v[24:27]
	v_mfma_f32_16x16x32_bf16 v[12:15], v[144:147], v[208:211], v[12:15]
	v_mfma_f32_16x16x32_bf16 v[8:11], v[160:163], v[208:211], v[8:11]
	v_mfma_f32_16x16x32_bf16 v[60:63], v[156:159], v[188:191], v[60:63]
	v_mfma_f32_16x16x32_bf16 v[56:59], v[164:167], v[188:191], v[56:59]
	v_mfma_f32_16x16x32_bf16 v[44:47], v[156:159], v[196:199], v[44:47]
	v_mfma_f32_16x16x32_bf16 v[40:43], v[164:167], v[196:199], v[40:43]
	v_mfma_f32_16x16x32_bf16 v[28:31], v[156:159], v[204:207], v[28:31]
	v_mfma_f32_16x16x32_bf16 v[24:27], v[164:167], v[204:207], v[24:27]
	v_mfma_f32_16x16x32_bf16 v[12:15], v[156:159], v[212:215], v[12:15]
	v_mfma_f32_16x16x32_bf16 v[8:11], v[164:167], v[212:215], v[8:11]
	v_mfma_f32_16x16x32_bf16 v[52:55], v[168:171], v[184:187], v[52:55]
	v_mfma_f32_16x16x32_bf16 v[48:51], v[176:179], v[184:187], v[48:51]
	v_mfma_f32_16x16x32_bf16 v[36:39], v[168:171], v[192:195], v[36:39]
	v_mfma_f32_16x16x32_bf16 v[32:35], v[176:179], v[192:195], v[32:35]
	v_mfma_f32_16x16x32_bf16 v[20:23], v[168:171], v[200:203], v[20:23]
	v_mfma_f32_16x16x32_bf16 v[16:19], v[176:179], v[200:203], v[16:19]
	v_mfma_f32_16x16x32_bf16 v[4:7], v[168:171], v[208:211], v[4:7]
	v_mfma_f32_16x16x32_bf16 v[0:3], v[176:179], v[208:211], v[0:3]
	v_mfma_f32_16x16x32_bf16 v[52:55], v[172:175], v[188:191], v[52:55]
	v_mfma_f32_16x16x32_bf16 v[48:51], v[180:183], v[188:191], v[48:51]
	v_mfma_f32_16x16x32_bf16 v[36:39], v[172:175], v[196:199], v[36:39]
	v_mfma_f32_16x16x32_bf16 v[32:35], v[180:183], v[196:199], v[32:35]
	v_mfma_f32_16x16x32_bf16 v[20:23], v[172:175], v[204:207], v[20:23]
	v_mfma_f32_16x16x32_bf16 v[16:19], v[180:183], v[204:207], v[16:19]
	v_mfma_f32_16x16x32_bf16 v[4:7], v[172:175], v[212:215], v[4:7]
	v_mfma_f32_16x16x32_bf16 v[0:3], v[180:183], v[212:215], v[0:3]
	s_barrier
	s_setprio 0
	s_add_i32 s76, s76, 2
	s_add_u32 s51, s51, 0x100
	s_addc_u32 s75, s75, 0
	s_cmp_gt_u32 s76, 13
	s_mov_b64 s[48:49], s[52:53]

.LBB0_551:
	v_readlane_b32 s4, v249, 0
	v_readlane_b32 s18, v249, 14
	v_readlane_b32 s19, v249, 15
	v_readlane_b32 s16, v249, 12
	v_readlane_b32 s17, v249, 13
	s_mov_b64 s[78:79], s[18:19]
	s_add_u32 s28, s78, 0x18a00000
	s_addc_u32 s29, s79, 0
	s_add_u32 s20, s78, 0x50000
	s_mov_b64 s[22:23], 0x80
	v_readlane_b32 s6, v249, 2
	s_addc_u32 s21, s79, 0
	s_lshl_b32 s1, s1, 5
	s_add_i32 m0, s59, 0x18000
	v_lshl_add_u64 v[4:5], v[4:5], 0, s[22:23]
	v_readlane_b32 s5, v249, 1
	s_mov_b64 s[76:77], s[16:17]
	s_lshl_b32 s6, s55, 13
	s_and_b32 s17, s1, 0x60
	s_waitcnt vmcnt(2)
	s_barrier
	global_load_lds_dwordx4 v[4:5], off
	v_lshl_add_u64 v[2:3], v[2:3], 0, s[22:23]
	s_add_i32 m0, s59, 0x1a000
	s_add_i32 s75, s59, 0x8000
	s_add_i32 s92, s59, 0xa000
	s_mov_b64 s[64:65], s[4:5]
	global_load_lds_dwordx4 v[2:3], off
	v_lshl_add_u64 v[0:1], v[0:1], 0, s[22:23]
	s_mov_b32 m0, s75
	s_add_u32 s4, s88, 0x40080
	global_load_lds_dwordx4 v[0:1], off
	v_lshl_add_u64 v[0:1], v[6:7], 0, s[22:23]
	s_mov_b32 m0, s92
	s_addc_u32 s5, s89, 0
	global_load_lds_dwordx4 v[0:1], off
	s_add_i32 m0, s59, 0x1c000
	v_lshl_add_u64 v[0:1], s[4:5], 0, v[164:165]
	global_load_lds_dwordx4 v[0:1], off
	v_lshl_add_u64 v[0:1], s[4:5], 0, v[166:167]
	s_add_i32 m0, s59, 0x1e000
	s_sext_i32_i16 s16, s0
	global_load_lds_dwordx4 v[0:1], off
	v_cmp_eq_u32_e64 s[0:1], 8, v181
	v_readlane_b32 s7, v249, 3
	v_readlane_b32 s8, v249, 4
	v_readlane_b32 s9, v249, 5
	v_readlane_b32 s10, v249, 6
	v_readlane_b32 s11, v249, 7
	v_readlane_b32 s12, v249, 8
	v_readlane_b32 s13, v249, 9
	v_readlane_b32 s14, v249, 10
	v_readlane_b32 s15, v249, 11
	v_writelane_b32 v249, s0, 16
	v_lshl_or_b32 v0, v181, 6, v183
	v_bitop3_b32 v2, s6, v0, v10 bitop3:0xf6
	v_writelane_b32 v249, s1, 17
	s_cmpk_lt_u32 s3, 0x100
	v_readlane_b32 s0, v249, 32
	s_cselect_b64 s[30:31], -1, 0
	s_ashr_i32 s93, s82, 31
	v_readlane_b32 s14, v249, 46
	v_readlane_b32 s15, v249, 47
	s_add_u32 s36, s14, 0x5800
	s_addc_u32 s37, s15, 0
	s_add_u32 s38, s14, 0xb000
	s_addc_u32 s39, s15, 0
	s_add_u32 s40, s14, 0x2c00
	s_addc_u32 s41, s15, 0
	s_add_u32 s42, s14, 0x8400
	s_addc_u32 s43, s15, 0
	s_add_u32 s44, s14, 0xdc00
	v_lshlrev_b32_e32 v0, 12, v219
	s_addc_u32 s45, s15, 0
	v_and_b32_e32 v0, 0x3c000, v0
	v_lshlrev_b32_e32 v1, 11, v11
	s_waitcnt vmcnt(6)
	v_readlane_b32 s1, v249, 33
	s_add_u32 s46, s64, 0x2c00
	v_or3_b32 v0, v8, v0, v1
	v_lshl_or_b32 v203, s17, 7, v185
	v_lshlrev_b32_e32 v204, 3, v181
	v_cmp_eq_u32_e32 vcc, 0, v181
	s_addc_u32 s47, s65, 0
	v_add_u32_e32 v0, v0, v9
	v_mov_b32_e32 v1, v165
	s_mov_b64 s[0:1], 0x2080
	s_add_i32 s95, 0, 0x10000
	s_add_i32 s96, 0, 0x14000
	v_cmp_eq_u32_e64 s[24:25], 7, v181
	v_or_b32_e32 v205, 7, v204
	s_mov_b32 s94, s82
	v_readlane_b32 s3, v249, 35
	v_or_b32_e32 v206, s17, v179
	v_lshl_add_u64 v[168:169], v[0:1], 0, s[0:1]
	v_mov_b64_e32 v[170:171], 0x1bee
	v_mov_b64_e32 v[172:173], 0x1bed
	v_add_u32_e32 v207, s95, v203
	v_add_u32_e32 v208, s96, v203
	v_add_u32_e32 v209, 0, v2
	v_mov_b32_e32 v210, 0x358637bd
	s_mov_b32 s48, 0x3f3504f3
	s_mov_b32 s97, 0xc07547cb
	s_mov_b32 s52, 0x39702d51
	s_mov_b32 s54, 0x3d50b6eb
	s_mov_b32 s56, 0x3e3da740
	s_mov_b32 s58, 0x3f906eba
	s_mov_b32 s60, 0x33fd3906
	s_mov_b32 s62, 0x3a856d28
	s_xor_b64 s[64:65], vcc, -1
	s_movk_i32 s34, 0x1600
	v_mov_b32_e32 v211, 0x407547cb
	s_mov_b32 s66, 0x3c6687d4
	s_mov_b32 s72, 0x3de34c21
	s_mov_b32 s74, 0x3efeb44a
	s_barrier
	v_readlane_b32 s2, v249, 34
	v_readlane_b32 s4, v249, 36
	v_readlane_b32 s5, v249, 37
	v_readlane_b32 s6, v249, 38
	v_readlane_b32 s7, v249, 39
	v_readlane_b32 s8, v249, 40
	v_readlane_b32 s9, v249, 41
	v_readlane_b32 s10, v249, 42
	v_readlane_b32 s11, v249, 43
	v_readlane_b32 s12, v249, 44
	v_readlane_b32 s13, v249, 45
	s_waitcnt vmcnt(0)
	s_branch .LBB0_554

.LBB0_564:
	s_ashr_i32 s77, s76, 31
	s_lshl_b64 s[50:51], s[76:77], 19
	s_add_u32 s82, s49, s50
	s_addc_u32 s83, s53, s51
	s_and_b64 s[0:1], s[0:1], exec
	s_cselect_b32 s13, s83, s89
	s_cselect_b32 s77, s82, s88
	v_lshl_add_u64 v[92:93], s[84:85], 0, v[168:169]
	s_add_u32 vcc_lo, s88, 0x100
	v_lshl_add_u64 v[130:131], v[92:93], 0, s[86:87]
	s_addc_u32 vcc_hi, s89, 0
	s_mov_b32 s50, -2
	s_mov_b64 s[0:1], 0
	ds_read_b128 v[132:135], v207
	ds_read_b128 v[136:139], v207 offset:1024
	ds_read_b128 v[140:143], v207 offset:2048
	ds_read_b128 v[144:147], v207 offset:3072
	ds_read_b128 v[148:151], v208
	ds_read_b128 v[152:155], v208 offset:1024
	ds_read_b128 v[156:159], v208 offset:2048
	ds_read_b128 v[174:177], v208 offset:3072
	s_add_u32 s51, s84, s0
	s_addc_u32 s68, s85, s1
	s_add_u32 s51, s51, 0x100
	s_addc_u32 s68, s68, 0
	s_add_u32 s69, vcc_lo, s0
	s_addc_u32 s70, vcc_hi, s1
	s_cmpk_eq_i32 s0, 0x700
	s_cselect_b32 s91, s79, s68
	s_cselect_b32 s90, s78, s51
	s_cselect_b32 s51, s81, s87
	s_cselect_b32 s71, s80, s86
	s_cselect_b32 s89, s13, s70
	s_cselect_b32 s88, s77, s69
	v_lshl_add_u64 v[160:161], v[92:93], 0, s[0:1]
	s_add_i32 m0, s59, 0xc000
	ds_read_b128 v[194:197], v209
	ds_read_b128 v[198:201], v209 offset:1024
	ds_read_b128 v[212:215], v209 offset:2048
	ds_read_b128 v[224:227], v209 offset:3072
	ds_read_b128 v[228:231], v209 offset:4096
	ds_read_b128 v[232:235], v209 offset:5120
	ds_read_b128 v[236:239], v209 offset:6144
	ds_read_b128 v[240:243], v209 offset:7168
	global_load_lds_dwordx4 v[160:161], off
	s_add_i32 m0, s59, 0xe000
	v_lshl_add_u64 v[160:161], v[130:131], 0, s[0:1]
	global_load_lds_dwordx4 v[160:161], off
	s_waitcnt vmcnt(14) lgkmcnt(0)
	s_setprio 1
	s_barrier
	v_mfma_f32_16x16x32_bf16 v[126:129], v[132:135], v[194:197], 0
	v_mfma_f32_16x16x32_bf16 v[60:63], v[140:143], v[194:197], 0
	v_mfma_f32_16x16x32_bf16 v[118:121], v[132:135], v[212:215], 0
	v_mfma_f32_16x16x32_bf16 v[52:55], v[140:143], v[212:215], 0
	v_mfma_f32_16x16x32_bf16 v[110:113], v[132:135], v[228:231], 0
	v_mfma_f32_16x16x32_bf16 v[44:47], v[140:143], v[228:231], 0
	v_mfma_f32_16x16x32_bf16 v[94:97], v[132:135], v[236:239], 0
	v_mfma_f32_16x16x32_bf16 v[28:31], v[140:143], v[236:239], 0
	v_mfma_f32_16x16x32_bf16 v[126:129], v[136:139], v[198:201], v[126:129]
	v_mfma_f32_16x16x32_bf16 v[60:63], v[144:147], v[198:201], v[60:63]
	v_mfma_f32_16x16x32_bf16 v[118:121], v[136:139], v[224:227], v[118:121]
	v_mfma_f32_16x16x32_bf16 v[52:55], v[144:147], v[224:227], v[52:55]
	v_mfma_f32_16x16x32_bf16 v[110:113], v[136:139], v[232:235], v[110:113]
	v_mfma_f32_16x16x32_bf16 v[44:47], v[144:147], v[232:235], v[44:47]
	v_mfma_f32_16x16x32_bf16 v[94:97], v[136:139], v[240:243], v[94:97]
	v_mfma_f32_16x16x32_bf16 v[28:31], v[144:147], v[240:243], v[28:31]
	v_mfma_f32_16x16x32_bf16 v[122:125], v[148:151], v[194:197], 0
	v_mfma_f32_16x16x32_bf16 v[56:59], v[156:159], v[194:197], 0
	v_mfma_f32_16x16x32_bf16 v[114:117], v[148:151], v[212:215], 0
	v_mfma_f32_16x16x32_bf16 v[48:51], v[156:159], v[212:215], 0
	v_mfma_f32_16x16x32_bf16 v[102:105], v[148:151], v[228:231], 0
	v_mfma_f32_16x16x32_bf16 v[36:39], v[156:159], v[228:231], 0
	v_mfma_f32_16x16x32_bf16 v[88:91], v[148:151], v[236:239], 0
	v_mfma_f32_16x16x32_bf16 v[24:27], v[156:159], v[236:239], 0
	v_mfma_f32_16x16x32_bf16 v[122:125], v[152:155], v[198:201], v[122:125]
	v_mfma_f32_16x16x32_bf16 v[56:59], v[174:177], v[198:201], v[56:59]
	v_mfma_f32_16x16x32_bf16 v[114:117], v[152:155], v[224:227], v[114:117]
	v_mfma_f32_16x16x32_bf16 v[48:51], v[174:177], v[224:227], v[48:51]
	v_mfma_f32_16x16x32_bf16 v[102:105], v[152:155], v[232:235], v[102:105]
	v_mfma_f32_16x16x32_bf16 v[36:39], v[174:177], v[232:235], v[36:39]
	v_mfma_f32_16x16x32_bf16 v[88:91], v[152:155], v[240:243], v[88:91]
	v_mfma_f32_16x16x32_bf16 v[24:27], v[174:177], v[240:243], v[24:27]
	s_barrier
	s_setprio 0
	s_add_i32 s68, s95, s57
	v_lshl_add_u64 v[160:161], s[88:89], 0, v[164:165]
	s_mov_b32 m0, s68
	ds_read_b128 v[194:197], v209 offset:16384
	ds_read_b128 v[198:201], v209 offset:17408
	ds_read_b128 v[212:215], v209 offset:18432
	ds_read_b128 v[224:227], v209 offset:19456
	ds_read_b128 v[228:231], v209 offset:20480
	ds_read_b128 v[232:235], v209 offset:21504
	ds_read_b128 v[236:239], v209 offset:22528
	ds_read_b128 v[240:243], v209 offset:23552
	global_load_lds_dwordx4 v[160:161], off
	s_add_i32 m0, s68, 0x2000
	s_add_u32 s68, s88, 0x40000
	v_lshl_add_u64 v[216:217], s[88:89], 0, v[166:167]
	s_addc_u32 s69, s89, 0
	s_add_i32 s70, s96, s57
	global_load_lds_dwordx4 v[216:217], off
	s_mov_b32 m0, s70
	v_lshl_add_u64 v[220:221], s[68:69], 0, v[164:165]
	global_load_lds_dwordx4 v[220:221], off
	s_add_i32 m0, s70, 0x2000
	v_lshl_add_u64 v[220:221], s[68:69], 0, v[166:167]
	s_add_u32 s68, s90, s71
	global_load_lds_dwordx4 v[220:221], off
	v_lshl_add_u64 v[220:221], s[90:91], 0, v[162:163]
	s_mov_b32 m0, s59
	s_addc_u32 s69, s91, s51
	global_load_lds_dwordx4 v[220:221], off
	s_mov_b32 m0, s61
	v_lshl_add_u64 v[244:245], s[68:69], 0, v[162:163]
	global_load_lds_dwordx4 v[244:245], off
	s_waitcnt vmcnt(14) lgkmcnt(0)
	s_setprio 1
	s_barrier
	v_mfma_f32_16x16x32_bf16 v[84:87], v[132:135], v[194:197], 0
	v_mfma_f32_16x16x32_bf16 v[20:23], v[140:143], v[194:197], 0
	v_mfma_f32_16x16x32_bf16 v[76:79], v[132:135], v[212:215], 0
	v_mfma_f32_16x16x32_bf16 v[12:15], v[140:143], v[212:215], 0
	v_mfma_f32_16x16x32_bf16 v[68:71], v[132:135], v[228:231], 0
	v_mfma_f32_16x16x32_bf16 v[4:7], v[140:143], v[228:231], 0
	v_mfma_f32_16x16x32_bf16 v[106:109], v[132:135], v[236:239], 0
	v_mfma_f32_16x16x32_bf16 v[40:43], v[140:143], v[236:239], 0
	v_mfma_f32_16x16x32_bf16 v[84:87], v[136:139], v[198:201], v[84:87]
	v_mfma_f32_16x16x32_bf16 v[20:23], v[144:147], v[198:201], v[20:23]
	v_mfma_f32_16x16x32_bf16 v[76:79], v[136:139], v[224:227], v[76:79]
	v_mfma_f32_16x16x32_bf16 v[12:15], v[144:147], v[224:227], v[12:15]
	v_mfma_f32_16x16x32_bf16 v[68:71], v[136:139], v[232:235], v[68:71]
	v_mfma_f32_16x16x32_bf16 v[4:7], v[144:147], v[232:235], v[4:7]
	v_mfma_f32_16x16x32_bf16 v[106:109], v[136:139], v[240:243], v[106:109]
	v_mfma_f32_16x16x32_bf16 v[40:43], v[144:147], v[240:243], v[40:43]
	v_mfma_f32_16x16x32_bf16 v[80:83], v[148:151], v[194:197], 0
	v_mfma_f32_16x16x32_bf16 v[16:19], v[156:159], v[194:197], 0
	v_mfma_f32_16x16x32_bf16 v[72:75], v[148:151], v[212:215], 0
	v_mfma_f32_16x16x32_bf16 v[8:11], v[156:159], v[212:215], 0
	v_mfma_f32_16x16x32_bf16 v[64:67], v[148:151], v[228:231], 0
	v_mfma_f32_16x16x32_bf16 v[0:3], v[156:159], v[228:231], 0
	v_mfma_f32_16x16x32_bf16 v[98:101], v[148:151], v[236:239], 0
	v_mfma_f32_16x16x32_bf16 v[32:35], v[156:159], v[236:239], 0
	v_mfma_f32_16x16x32_bf16 v[80:83], v[152:155], v[198:201], v[80:83]
	v_mfma_f32_16x16x32_bf16 v[16:19], v[174:177], v[198:201], v[16:19]
	v_mfma_f32_16x16x32_bf16 v[72:75], v[152:155], v[224:227], v[72:75]
	v_mfma_f32_16x16x32_bf16 v[8:11], v[174:177], v[224:227], v[8:11]
	v_mfma_f32_16x16x32_bf16 v[64:67], v[152:155], v[232:235], v[64:67]
	v_mfma_f32_16x16x32_bf16 v[0:3], v[174:177], v[232:235], v[0:3]
	v_mfma_f32_16x16x32_bf16 v[98:101], v[152:155], v[240:243], v[98:101]
	v_mfma_f32_16x16x32_bf16 v[32:35], v[174:177], v[240:243], v[32:35]
	s_barrier
	s_setprio 0
	s_add_i32 s70, 0, 0x18000
	s_add_i32 s14, 0, 0x1c000
	v_add_u32_e32 v144, s70, v203
	v_add_u32_e32 v174, s14, v203
	ds_read_b128 v[132:135], v144
	ds_read_b128 v[136:139], v144 offset:1024
	ds_read_b128 v[140:143], v144 offset:2048
	ds_read_b128 v[144:147], v144 offset:3072
	ds_read_b128 v[148:151], v174
	ds_read_b128 v[152:155], v174 offset:1024
	ds_read_b128 v[156:159], v174 offset:2048
	ds_read_b128 v[174:177], v174 offset:3072
	s_add_u32 s68, s90, 0x2000
	s_addc_u32 s69, s91, 0
	v_lshl_add_u64 v[246:247], s[68:69], 0, v[162:163]
	s_add_u32 s68, s68, s71
	s_mov_b32 m0, s63
	s_addc_u32 s69, s69, s51
	ds_read_b128 v[194:197], v209 offset:32768
	ds_read_b128 v[198:201], v209 offset:33792
	ds_read_b128 v[212:215], v209 offset:34816
	ds_read_b128 v[224:227], v209 offset:35840
	ds_read_b128 v[228:231], v209 offset:36864
	ds_read_b128 v[232:235], v209 offset:37888
	ds_read_b128 v[236:239], v209 offset:38912
	ds_read_b128 v[240:243], v209 offset:39936
	global_load_lds_dwordx4 v[246:247], off
	s_mov_b32 m0, s67
	v_lshl_add_u64 v[246:247], s[68:69], 0, v[162:163]
	global_load_lds_dwordx4 v[246:247], off
	s_waitcnt vmcnt(8) lgkmcnt(0)
	s_setprio 1
	s_barrier
	v_mfma_f32_16x16x32_bf16 v[126:129], v[132:135], v[194:197], v[126:129]
	v_mfma_f32_16x16x32_bf16 v[60:63], v[140:143], v[194:197], v[60:63]
	v_mfma_f32_16x16x32_bf16 v[118:121], v[132:135], v[212:215], v[118:121]
	v_mfma_f32_16x16x32_bf16 v[52:55], v[140:143], v[212:215], v[52:55]
	v_mfma_f32_16x16x32_bf16 v[110:113], v[132:135], v[228:231], v[110:113]
	v_mfma_f32_16x16x32_bf16 v[44:47], v[140:143], v[228:231], v[44:47]
	v_mfma_f32_16x16x32_bf16 v[94:97], v[132:135], v[236:239], v[94:97]
	v_mfma_f32_16x16x32_bf16 v[28:31], v[140:143], v[236:239], v[28:31]
	v_mfma_f32_16x16x32_bf16 v[126:129], v[136:139], v[198:201], v[126:129]
	v_mfma_f32_16x16x32_bf16 v[60:63], v[144:147], v[198:201], v[60:63]
	v_mfma_f32_16x16x32_bf16 v[118:121], v[136:139], v[224:227], v[118:121]
	v_mfma_f32_16x16x32_bf16 v[52:55], v[144:147], v[224:227], v[52:55]
	v_mfma_f32_16x16x32_bf16 v[110:113], v[136:139], v[232:235], v[110:113]
	v_mfma_f32_16x16x32_bf16 v[44:47], v[144:147], v[232:235], v[44:47]
	v_mfma_f32_16x16x32_bf16 v[94:97], v[136:139], v[240:243], v[94:97]
	v_mfma_f32_16x16x32_bf16 v[28:31], v[144:147], v[240:243], v[28:31]
	v_mfma_f32_16x16x32_bf16 v[122:125], v[148:151], v[194:197], v[122:125]
	v_mfma_f32_16x16x32_bf16 v[56:59], v[156:159], v[194:197], v[56:59]
	v_mfma_f32_16x16x32_bf16 v[114:117], v[148:151], v[212:215], v[114:117]
	v_mfma_f32_16x16x32_bf16 v[48:51], v[156:159], v[212:215], v[48:51]
	v_mfma_f32_16x16x32_bf16 v[102:105], v[148:151], v[228:231], v[102:105]
	v_mfma_f32_16x16x32_bf16 v[36:39], v[156:159], v[228:231], v[36:39]
	v_mfma_f32_16x16x32_bf16 v[88:91], v[148:151], v[236:239], v[88:91]
	v_mfma_f32_16x16x32_bf16 v[24:27], v[156:159], v[236:239], v[24:27]
	v_mfma_f32_16x16x32_bf16 v[122:125], v[152:155], v[198:201], v[122:125]
	v_mfma_f32_16x16x32_bf16 v[56:59], v[174:177], v[198:201], v[56:59]
	v_mfma_f32_16x16x32_bf16 v[114:117], v[152:155], v[224:227], v[114:117]
	v_mfma_f32_16x16x32_bf16 v[48:51], v[174:177], v[224:227], v[48:51]
	v_mfma_f32_16x16x32_bf16 v[102:105], v[152:155], v[232:235], v[102:105]
	v_mfma_f32_16x16x32_bf16 v[36:39], v[174:177], v[232:235], v[36:39]
	v_mfma_f32_16x16x32_bf16 v[88:91], v[152:155], v[240:243], v[88:91]
	v_mfma_f32_16x16x32_bf16 v[24:27], v[174:177], v[240:243], v[24:27]
	s_barrier
	s_setprio 0
	s_add_i32 s15, s70, s57
	v_lshl_add_u64 v[160:161], v[160:161], 0, s[22:23]
	s_mov_b32 m0, s15
	ds_read_b128 v[194:197], v209 offset:49152
	ds_read_b128 v[198:201], v209 offset:50176
	ds_read_b128 v[212:215], v209 offset:51200
	ds_read_b128 v[224:227], v209 offset:52224
	ds_read_b128 v[228:231], v209 offset:53248
	ds_read_b128 v[232:235], v209 offset:54272
	ds_read_b128 v[236:239], v209 offset:55296
	ds_read_b128 v[240:243], v209 offset:56320
	global_load_lds_dwordx4 v[160:161], off
	s_add_i32 m0, s15, 0x2000
	s_add_u32 s68, s88, 0x40080
	v_lshl_add_u64 v[160:161], v[216:217], 0, s[22:23]
	s_addc_u32 s69, s89, 0
	s_add_i32 s14, s14, s57
	global_load_lds_dwordx4 v[160:161], off
	s_mov_b32 m0, s14
	v_lshl_add_u64 v[160:161], s[68:69], 0, v[164:165]
	global_load_lds_dwordx4 v[160:161], off
	s_add_i32 m0, s14, 0x2000
	v_lshl_add_u64 v[160:161], s[68:69], 0, v[166:167]
	global_load_lds_dwordx4 v[160:161], off
	s_mov_b32 m0, s75
	v_lshl_add_u64 v[160:161], v[220:221], 0, s[22:23]
	global_load_lds_dwordx4 v[160:161], off
	s_mov_b32 m0, s92
	v_lshl_add_u64 v[160:161], v[244:245], 0, s[22:23]
	global_load_lds_dwordx4 v[160:161], off
	s_waitcnt vmcnt(8) lgkmcnt(0)
	s_setprio 1
	s_barrier
	v_mfma_f32_16x16x32_bf16 v[84:87], v[132:135], v[194:197], v[84:87]
	v_mfma_f32_16x16x32_bf16 v[20:23], v[140:143], v[194:197], v[20:23]
	v_mfma_f32_16x16x32_bf16 v[76:79], v[132:135], v[212:215], v[76:79]
	v_mfma_f32_16x16x32_bf16 v[12:15], v[140:143], v[212:215], v[12:15]
	v_mfma_f32_16x16x32_bf16 v[68:71], v[132:135], v[228:231], v[68:71]
	v_mfma_f32_16x16x32_bf16 v[4:7], v[140:143], v[228:231], v[4:7]
	v_mfma_f32_16x16x32_bf16 v[106:109], v[132:135], v[236:239], v[106:109]
	v_mfma_f32_16x16x32_bf16 v[40:43], v[140:143], v[236:239], v[40:43]
	v_mfma_f32_16x16x32_bf16 v[84:87], v[136:139], v[198:201], v[84:87]
	v_mfma_f32_16x16x32_bf16 v[20:23], v[144:147], v[198:201], v[20:23]
	v_mfma_f32_16x16x32_bf16 v[76:79], v[136:139], v[224:227], v[76:79]
	v_mfma_f32_16x16x32_bf16 v[12:15], v[144:147], v[224:227], v[12:15]
	v_mfma_f32_16x16x32_bf16 v[68:71], v[136:139], v[232:235], v[68:71]
	v_mfma_f32_16x16x32_bf16 v[4:7], v[144:147], v[232:235], v[4:7]
	v_mfma_f32_16x16x32_bf16 v[106:109], v[136:139], v[240:243], v[106:109]
	v_mfma_f32_16x16x32_bf16 v[40:43], v[144:147], v[240:243], v[40:43]
	v_mfma_f32_16x16x32_bf16 v[80:83], v[148:151], v[194:197], v[80:83]
	v_mfma_f32_16x16x32_bf16 v[16:19], v[156:159], v[194:197], v[16:19]
	v_mfma_f32_16x16x32_bf16 v[72:75], v[148:151], v[212:215], v[72:75]
	v_mfma_f32_16x16x32_bf16 v[8:11], v[156:159], v[212:215], v[8:11]
	v_mfma_f32_16x16x32_bf16 v[64:67], v[148:151], v[228:231], v[64:67]
	v_mfma_f32_16x16x32_bf16 v[0:3], v[156:159], v[228:231], v[0:3]
	v_mfma_f32_16x16x32_bf16 v[98:101], v[148:151], v[236:239], v[98:101]
	v_mfma_f32_16x16x32_bf16 v[32:35], v[156:159], v[236:239], v[32:35]
	v_mfma_f32_16x16x32_bf16 v[80:83], v[152:155], v[198:201], v[80:83]
	v_mfma_f32_16x16x32_bf16 v[16:19], v[174:177], v[198:201], v[16:19]
	v_mfma_f32_16x16x32_bf16 v[72:75], v[152:155], v[224:227], v[72:75]
	v_mfma_f32_16x16x32_bf16 v[8:11], v[174:177], v[224:227], v[8:11]
	v_mfma_f32_16x16x32_bf16 v[64:67], v[152:155], v[232:235], v[64:67]
	v_mfma_f32_16x16x32_bf16 v[0:3], v[174:177], v[232:235], v[0:3]
	v_mfma_f32_16x16x32_bf16 v[98:101], v[152:155], v[240:243], v[98:101]
	v_mfma_f32_16x16x32_bf16 v[32:35], v[174:177], v[240:243], v[32:35]
	s_barrier
	s_setprio 0
	s_add_i32 s50, s50, 2
	s_add_u32 s0, s0, 0x100
	s_addc_u32 s1, s1, 0
	s_cmp_gt_u32 s50, 13

.LBB0_652:
	v_readlane_b32 s72, v249, 0
	v_readlane_b32 s84, v249, 12
	v_readlane_b32 s85, v249, 13
	v_readlane_b32 s86, v249, 14
	v_readlane_b32 s87, v249, 15
	s_mov_b64 s[24:25], s[84:85]
	s_mov_b64 s[26:27], s[86:87]
	s_add_u32 s20, s26, 0x4900000
	s_addc_u32 s21, s27, 0
	s_add_u32 s22, s26, 0xa0000
	s_addc_u32 s23, s27, 0
	s_lshl_b32 s1, s1, 5
	s_mov_b64 s[24:25], 0x80
	s_and_b32 s40, s1, 0x60
	s_add_i32 m0, s48, 0x18000
	v_lshl_add_u64 v[4:5], v[4:5], 0, s[24:25]
	s_lshl_b32 s5, s0, 13
	s_lshl_b32 s1, s40, 7
	s_waitcnt vmcnt(2)
	s_barrier
	global_load_lds_dwordx4 v[4:5], off
	v_lshl_add_u64 v[4:5], v[6:7], 0, s[24:25]
	s_add_i32 m0, s48, 0x1a000
	s_add_i32 s53, s48, 0x8000
	s_add_i32 s54, s48, 0xa000
	global_load_lds_dwordx4 v[4:5], off
	v_lshl_add_u64 v[0:1], v[0:1], 0, s[24:25]
	s_mov_b32 m0, s53
	s_mov_b64 s[36:37], 0x58080
	s_add_u32 s6, s44, 0xb0080
	global_load_lds_dwordx4 v[0:1], off
	v_lshl_add_u64 v[0:1], v[2:3], 0, s[36:37]
	s_mov_b32 m0, s54
	s_addc_u32 s7, s45, 0
	global_load_lds_dwordx4 v[0:1], off
	s_add_i32 m0, s48, 0x1c000
	v_lshl_add_u64 v[0:1], s[6:7], 0, v[130:131]
	global_load_lds_dwordx4 v[0:1], off
	v_lshl_add_u64 v[0:1], s[6:7], 0, v[134:135]
	s_add_i32 m0, s48, 0x1e000
	v_lshlrev_b32_e32 v3, 2, v219
	global_load_lds_dwordx4 v[0:1], off
	v_bfe_u32 v0, v219, 4, 2
	v_and_b32_e32 v1, 15, v219
	v_lshlrev_b32_e32 v2, 4, v0
	v_lshl_or_b32 v148, s0, 6, v1
	v_lshl_or_b32 v1, v1, 6, v2
	v_and_b32_e32 v3, 32, v3
	v_bitop3_b32 v4, v1, s5, v3 bitop3:0xde
	v_lshlrev_b32_e32 v1, 6, v219
	s_movk_i32 s0, 0x3c0
	v_cmp_eq_u32_e64 s[6:7], 0, v0
	v_lshl_or_b32 v150, v0, 3, s40
	v_add_u16_e32 v0, v8, v9
	v_and_or_b32 v1, v1, s0, v2
	v_lshrrev_b16_e32 v2, 1, v0
	v_readlane_b32 s80, v249, 8
	v_readlane_b32 s81, v249, 9
	v_readlane_b32 s82, v249, 10
	v_readlane_b32 s83, v249, 11
	v_bitop3_b32 v149, s1, v1, v3 bitop3:0xf6
	s_mov_b64 s[0:1], 0xb0080
	v_add_lshl_u32 v0, v10, v2, 1
	v_mov_b32_e32 v1, v131
	s_waitcnt vmcnt(6)
	s_cmpk_lt_u32 s4, 0x100
	s_mov_b64 s[80:81], s[88:89]
	v_lshl_add_u64 v[136:137], v[0:1], 0, s[0:1]
	v_add_lshl_u32 v0, v11, v2, 1
	s_mov_b64 s[0:1], 0x108080
	s_cselect_b64 s[38:39], -1, 0
	s_mov_b64 s[82:83], s[90:91]
	v_lshl_add_u64 v[138:139], v[0:1], 0, s[0:1]
	s_add_i32 s59, 0, 0x10000
	s_add_i32 s60, 0, 0x14000
	v_mbcnt_lo_u32_b32 v0, -1, 0
	s_ashr_i32 s55, s82, 31
	s_mov_b32 s56, s82
	s_ashr_i32 s57, s2, 31
	v_mov_b64_e32 v[140:141], 0x500
	v_mov_b64_e32 v[142:143], 0x4ff
	s_movk_i32 s58, 0xa1
	v_add_u32_e32 v151, s59, v149
	v_add_u32_e32 v152, s60, v149
	v_add_u32_e32 v153, 0, v4
	v_mbcnt_hi_u32_b32 v154, -1, v0
	v_readlane_b32 s73, v249, 1
	v_readlane_b32 s74, v249, 2
	v_readlane_b32 s75, v249, 3
	v_readlane_b32 s76, v249, 4
	v_readlane_b32 s77, v249, 5
	v_readlane_b32 s78, v249, 6
	v_readlane_b32 s79, v249, 7
	s_barrier
	s_waitcnt vmcnt(0)
	s_branch .LBB0_655

.LBB0_661:
	s_add_u32 s64, s44, 0x100
	s_addc_u32 s65, s45, 0
	s_mov_b32 s66, -2
	s_waitcnt lgkmcnt(0)
	ds_read_b128 v[144:147], v151
	ds_read_b128 v[156:159], v151 offset:1024
	ds_read_b128 v[160:163], v151 offset:2048
	ds_read_b128 v[164:167], v151 offset:3072
	ds_read_b128 v[168:171], v152
	ds_read_b128 v[172:175], v152 offset:1024
	ds_read_b128 v[176:179], v152 offset:2048
	ds_read_b128 v[180:183], v152 offset:3072
	s_add_u32 s44, s42, 0x100
	s_addc_u32 s45, s43, 0
	s_cmp_eq_u32 s66, 40
	s_cselect_b32 s69, s1, s45
	s_cselect_b32 s68, s0, s44
	s_cselect_b32 s47, s41, s65
	s_cselect_b32 s46, s40, s64
	v_lshl_add_u64 v[216:217], s[42:43], 0, v[136:137]
	s_add_i32 m0, s48, 0xc000
	ds_read_b128 v[184:187], v153
	ds_read_b128 v[188:191], v153 offset:1024
	ds_read_b128 v[192:195], v153 offset:2048
	ds_read_b128 v[196:199], v153 offset:3072
	ds_read_b128 v[200:203], v153 offset:4096
	ds_read_b128 v[204:207], v153 offset:5120
	ds_read_b128 v[208:211], v153 offset:6144
	ds_read_b128 v[212:215], v153 offset:7168
	global_load_lds_dwordx4 v[216:217], off
	s_add_i32 m0, s48, 0xe000
	v_lshl_add_u64 v[216:217], s[42:43], 0, v[138:139]
	global_load_lds_dwordx4 v[216:217], off
	s_waitcnt vmcnt(24) lgkmcnt(0)
	s_setprio 1
	s_barrier
	v_mfma_f32_16x16x32_bf16 v[124:127], v[144:147], v[184:187], 0
	v_mfma_f32_16x16x32_bf16 v[120:123], v[160:163], v[184:187], 0
	v_mfma_f32_16x16x32_bf16 v[108:111], v[144:147], v[192:195], 0
	v_mfma_f32_16x16x32_bf16 v[104:107], v[160:163], v[192:195], 0
	v_mfma_f32_16x16x32_bf16 v[92:95], v[144:147], v[200:203], 0
	v_mfma_f32_16x16x32_bf16 v[88:91], v[160:163], v[200:203], 0
	v_mfma_f32_16x16x32_bf16 v[76:79], v[144:147], v[208:211], 0
	v_mfma_f32_16x16x32_bf16 v[72:75], v[160:163], v[208:211], 0
	v_mfma_f32_16x16x32_bf16 v[124:127], v[156:159], v[188:191], v[124:127]
	v_mfma_f32_16x16x32_bf16 v[120:123], v[164:167], v[188:191], v[120:123]
	v_mfma_f32_16x16x32_bf16 v[108:111], v[156:159], v[196:199], v[108:111]
	v_mfma_f32_16x16x32_bf16 v[104:107], v[164:167], v[196:199], v[104:107]
	v_mfma_f32_16x16x32_bf16 v[92:95], v[156:159], v[204:207], v[92:95]
	v_mfma_f32_16x16x32_bf16 v[88:91], v[164:167], v[204:207], v[88:91]
	v_mfma_f32_16x16x32_bf16 v[76:79], v[156:159], v[212:215], v[76:79]
	v_mfma_f32_16x16x32_bf16 v[72:75], v[164:167], v[212:215], v[72:75]
	v_mfma_f32_16x16x32_bf16 v[116:119], v[168:171], v[184:187], 0
	v_mfma_f32_16x16x32_bf16 v[112:115], v[176:179], v[184:187], 0
	v_mfma_f32_16x16x32_bf16 v[100:103], v[168:171], v[192:195], 0
	v_mfma_f32_16x16x32_bf16 v[96:99], v[176:179], v[192:195], 0
	v_mfma_f32_16x16x32_bf16 v[84:87], v[168:171], v[200:203], 0
	v_mfma_f32_16x16x32_bf16 v[80:83], v[176:179], v[200:203], 0
	v_mfma_f32_16x16x32_bf16 v[68:71], v[168:171], v[208:211], 0
	v_mfma_f32_16x16x32_bf16 v[64:67], v[176:179], v[208:211], 0
	v_mfma_f32_16x16x32_bf16 v[116:119], v[172:175], v[188:191], v[116:119]
	v_mfma_f32_16x16x32_bf16 v[112:115], v[180:183], v[188:191], v[112:115]
	v_mfma_f32_16x16x32_bf16 v[100:103], v[172:175], v[196:199], v[100:103]
	v_mfma_f32_16x16x32_bf16 v[96:99], v[180:183], v[196:199], v[96:99]
	v_mfma_f32_16x16x32_bf16 v[84:87], v[172:175], v[204:207], v[84:87]
	v_mfma_f32_16x16x32_bf16 v[80:83], v[180:183], v[204:207], v[80:83]
	v_mfma_f32_16x16x32_bf16 v[68:71], v[172:175], v[212:215], v[68:71]
	v_mfma_f32_16x16x32_bf16 v[64:67], v[180:183], v[212:215], v[64:67]
	s_barrier
	s_setprio 0
	s_add_i32 s42, s59, s35
	v_lshl_add_u64 v[216:217], s[46:47], 0, v[130:131]
	s_mov_b32 m0, s42
	ds_read_b128 v[184:187], v153 offset:16384
	ds_read_b128 v[188:191], v153 offset:17408
	ds_read_b128 v[192:195], v153 offset:18432
	ds_read_b128 v[196:199], v153 offset:19456
	ds_read_b128 v[200:203], v153 offset:20480
	ds_read_b128 v[204:207], v153 offset:21504
	ds_read_b128 v[208:211], v153 offset:22528
	ds_read_b128 v[212:215], v153 offset:23552
	global_load_lds_dwordx4 v[216:217], off
	s_add_i32 m0, s42, 0x2000
	s_add_u32 s42, s46, 0xb0000
	v_lshl_add_u64 v[220:221], s[46:47], 0, v[134:135]
	s_addc_u32 s43, s47, 0
	s_add_i32 s67, s60, s35
	global_load_lds_dwordx4 v[220:221], off
	v_lshl_add_u64 v[224:225], s[42:43], 0, v[130:131]
	s_mov_b32 m0, s67
	v_lshl_add_u64 v[226:227], s[68:69], 0, v[132:133]
	global_load_lds_dwordx4 v[224:225], off
	v_lshl_add_u64 v[224:225], s[42:43], 0, v[134:135]
	s_add_i32 m0, s67, 0x2000
	v_lshl_add_u64 v[228:229], v[226:227], 0, s[14:15]
	global_load_lds_dwordx4 v[224:225], off
	s_mov_b32 m0, s48
	v_lshl_add_u64 v[224:225], s[68:69], 0, v[128:129]
	global_load_lds_dwordx4 v[224:225], off
	s_mov_b32 m0, s49
	s_nop 0
	global_load_lds_dwordx4 v[228:229], off
	s_waitcnt vmcnt(24) lgkmcnt(0)
	s_setprio 1
	s_barrier
	v_mfma_f32_16x16x32_bf16 v[60:63], v[144:147], v[184:187], 0
	v_mfma_f32_16x16x32_bf16 v[56:59], v[160:163], v[184:187], 0
	v_mfma_f32_16x16x32_bf16 v[44:47], v[144:147], v[192:195], 0
	v_mfma_f32_16x16x32_bf16 v[40:43], v[160:163], v[192:195], 0
	v_mfma_f32_16x16x32_bf16 v[28:31], v[144:147], v[200:203], 0
	v_mfma_f32_16x16x32_bf16 v[24:27], v[160:163], v[200:203], 0
	v_mfma_f32_16x16x32_bf16 v[12:15], v[144:147], v[208:211], 0
	v_mfma_f32_16x16x32_bf16 v[8:11], v[160:163], v[208:211], 0
	v_mfma_f32_16x16x32_bf16 v[60:63], v[156:159], v[188:191], v[60:63]
	v_mfma_f32_16x16x32_bf16 v[56:59], v[164:167], v[188:191], v[56:59]
	v_mfma_f32_16x16x32_bf16 v[44:47], v[156:159], v[196:199], v[44:47]
	v_mfma_f32_16x16x32_bf16 v[40:43], v[164:167], v[196:199], v[40:43]
	v_mfma_f32_16x16x32_bf16 v[28:31], v[156:159], v[204:207], v[28:31]
	v_mfma_f32_16x16x32_bf16 v[24:27], v[164:167], v[204:207], v[24:27]
	v_mfma_f32_16x16x32_bf16 v[12:15], v[156:159], v[212:215], v[12:15]
	v_mfma_f32_16x16x32_bf16 v[8:11], v[164:167], v[212:215], v[8:11]
	v_mfma_f32_16x16x32_bf16 v[52:55], v[168:171], v[184:187], 0
	v_mfma_f32_16x16x32_bf16 v[48:51], v[176:179], v[184:187], 0
	v_mfma_f32_16x16x32_bf16 v[36:39], v[168:171], v[192:195], 0
	v_mfma_f32_16x16x32_bf16 v[32:35], v[176:179], v[192:195], 0
	v_mfma_f32_16x16x32_bf16 v[20:23], v[168:171], v[200:203], 0
	v_mfma_f32_16x16x32_bf16 v[16:19], v[176:179], v[200:203], 0
	v_mfma_f32_16x16x32_bf16 v[4:7], v[168:171], v[208:211], 0
	v_mfma_f32_16x16x32_bf16 v[0:3], v[176:179], v[208:211], 0
	v_mfma_f32_16x16x32_bf16 v[52:55], v[172:175], v[188:191], v[52:55]
	v_mfma_f32_16x16x32_bf16 v[48:51], v[180:183], v[188:191], v[48:51]
	v_mfma_f32_16x16x32_bf16 v[36:39], v[172:175], v[196:199], v[36:39]
	v_mfma_f32_16x16x32_bf16 v[32:35], v[180:183], v[196:199], v[32:35]
	v_mfma_f32_16x16x32_bf16 v[20:23], v[172:175], v[204:207], v[20:23]
	v_mfma_f32_16x16x32_bf16 v[16:19], v[180:183], v[204:207], v[16:19]
	v_mfma_f32_16x16x32_bf16 v[4:7], v[172:175], v[212:215], v[4:7]
	v_mfma_f32_16x16x32_bf16 v[0:3], v[180:183], v[212:215], v[0:3]
	s_barrier
	s_setprio 0
	s_add_i32 s42, 0, 0x18000
	v_add_u32_e32 v155, s42, v149
	s_add_i32 s67, 0, 0x1c000
	ds_read_b128 v[144:147], v155
	ds_read_b128 v[156:159], v155 offset:1024
	ds_read_b128 v[160:163], v155 offset:2048
	ds_read_b128 v[164:167], v155 offset:3072
	v_add_u32_e32 v155, s67, v149
	ds_read_b128 v[168:171], v155
	ds_read_b128 v[172:175], v155 offset:1024
	ds_read_b128 v[176:179], v155 offset:2048
	ds_read_b128 v[180:183], v155 offset:3072
	s_mov_b32 m0, s50
	v_lshl_add_u64 v[228:229], v[224:225], 0, s[12:13]
	ds_read_b128 v[184:187], v153 offset:32768
	ds_read_b128 v[188:191], v153 offset:33792
	ds_read_b128 v[192:195], v153 offset:34816
	ds_read_b128 v[196:199], v153 offset:35840
	ds_read_b128 v[200:203], v153 offset:36864
	ds_read_b128 v[204:207], v153 offset:37888
	ds_read_b128 v[208:211], v153 offset:38912
	ds_read_b128 v[212:215], v153 offset:39936
	global_load_lds_dwordx4 v[228:229], off
	s_mov_b32 m0, s51
	v_lshl_add_u64 v[228:229], v[226:227], 0, s[16:17]
	global_load_lds_dwordx4 v[228:229], off
	s_waitcnt vmcnt(8) lgkmcnt(0)
	s_setprio 1
	s_barrier
	v_mfma_f32_16x16x32_bf16 v[124:127], v[144:147], v[184:187], v[124:127]
	v_mfma_f32_16x16x32_bf16 v[120:123], v[160:163], v[184:187], v[120:123]
	v_mfma_f32_16x16x32_bf16 v[108:111], v[144:147], v[192:195], v[108:111]
	v_mfma_f32_16x16x32_bf16 v[104:107], v[160:163], v[192:195], v[104:107]
	v_mfma_f32_16x16x32_bf16 v[92:95], v[144:147], v[200:203], v[92:95]
	v_mfma_f32_16x16x32_bf16 v[88:91], v[160:163], v[200:203], v[88:91]
	v_mfma_f32_16x16x32_bf16 v[76:79], v[144:147], v[208:211], v[76:79]
	v_mfma_f32_16x16x32_bf16 v[72:75], v[160:163], v[208:211], v[72:75]
	v_mfma_f32_16x16x32_bf16 v[124:127], v[156:159], v[188:191], v[124:127]
	v_mfma_f32_16x16x32_bf16 v[120:123], v[164:167], v[188:191], v[120:123]
	v_mfma_f32_16x16x32_bf16 v[108:111], v[156:159], v[196:199], v[108:111]
	v_mfma_f32_16x16x32_bf16 v[104:107], v[164:167], v[196:199], v[104:107]
	v_mfma_f32_16x16x32_bf16 v[92:95], v[156:159], v[204:207], v[92:95]
	v_mfma_f32_16x16x32_bf16 v[88:91], v[164:167], v[204:207], v[88:91]
	v_mfma_f32_16x16x32_bf16 v[76:79], v[156:159], v[212:215], v[76:79]
	v_mfma_f32_16x16x32_bf16 v[72:75], v[164:167], v[212:215], v[72:75]
	v_mfma_f32_16x16x32_bf16 v[116:119], v[168:171], v[184:187], v[116:119]
	v_mfma_f32_16x16x32_bf16 v[112:115], v[176:179], v[184:187], v[112:115]
	v_mfma_f32_16x16x32_bf16 v[100:103], v[168:171], v[192:195], v[100:103]
	v_mfma_f32_16x16x32_bf16 v[96:99], v[176:179], v[192:195], v[96:99]
	v_mfma_f32_16x16x32_bf16 v[84:87], v[168:171], v[200:203], v[84:87]
	v_mfma_f32_16x16x32_bf16 v[80:83], v[176:179], v[200:203], v[80:83]
	v_mfma_f32_16x16x32_bf16 v[68:71], v[168:171], v[208:211], v[68:71]
	v_mfma_f32_16x16x32_bf16 v[64:67], v[176:179], v[208:211], v[64:67]
	v_mfma_f32_16x16x32_bf16 v[116:119], v[172:175], v[188:191], v[116:119]
	v_mfma_f32_16x16x32_bf16 v[112:115], v[180:183], v[188:191], v[112:115]
	v_mfma_f32_16x16x32_bf16 v[100:103], v[172:175], v[196:199], v[100:103]
	v_mfma_f32_16x16x32_bf16 v[96:99], v[180:183], v[196:199], v[96:99]
	v_mfma_f32_16x16x32_bf16 v[84:87], v[172:175], v[204:207], v[84:87]
	v_mfma_f32_16x16x32_bf16 v[80:83], v[180:183], v[204:207], v[80:83]
	v_mfma_f32_16x16x32_bf16 v[68:71], v[172:175], v[212:215], v[68:71]
	v_mfma_f32_16x16x32_bf16 v[64:67], v[180:183], v[212:215], v[64:67]
	s_barrier
	s_setprio 0
	s_add_i32 s42, s42, s35
	v_lshl_add_u64 v[216:217], v[216:217], 0, s[24:25]
	s_mov_b32 m0, s42
	ds_read_b128 v[184:187], v153 offset:49152
	ds_read_b128 v[188:191], v153 offset:50176
	ds_read_b128 v[192:195], v153 offset:51200
	ds_read_b128 v[196:199], v153 offset:52224
	ds_read_b128 v[200:203], v153 offset:53248
	ds_read_b128 v[204:207], v153 offset:54272
	ds_read_b128 v[208:211], v153 offset:55296
	ds_read_b128 v[212:215], v153 offset:56320
	global_load_lds_dwordx4 v[216:217], off
	s_add_i32 m0, s42, 0x2000
	s_add_u32 s42, s46, 0xb0080
	v_lshl_add_u64 v[216:217], v[220:221], 0, s[24:25]
	s_addc_u32 s43, s47, 0
	s_add_i32 s46, s67, s35
	global_load_lds_dwordx4 v[216:217], off
	s_mov_b32 m0, s46
	v_lshl_add_u64 v[216:217], s[42:43], 0, v[130:131]
	global_load_lds_dwordx4 v[216:217], off
	s_add_i32 m0, s46, 0x2000
	v_lshl_add_u64 v[216:217], s[42:43], 0, v[134:135]
	global_load_lds_dwordx4 v[216:217], off
	s_mov_b32 m0, s53
	v_lshl_add_u64 v[216:217], v[224:225], 0, s[24:25]
	global_load_lds_dwordx4 v[216:217], off
	s_mov_b32 m0, s54
	v_lshl_add_u64 v[216:217], v[226:227], 0, s[36:37]
	global_load_lds_dwordx4 v[216:217], off
	s_waitcnt vmcnt(8) lgkmcnt(0)
	s_setprio 1
	s_barrier
	v_mfma_f32_16x16x32_bf16 v[60:63], v[144:147], v[184:187], v[60:63]
	v_mfma_f32_16x16x32_bf16 v[56:59], v[160:163], v[184:187], v[56:59]
	v_mfma_f32_16x16x32_bf16 v[44:47], v[144:147], v[192:195], v[44:47]
	v_mfma_f32_16x16x32_bf16 v[40:43], v[160:163], v[192:195], v[40:43]
	v_mfma_f32_16x16x32_bf16 v[28:31], v[144:147], v[200:203], v[28:31]
	v_mfma_f32_16x16x32_bf16 v[24:27], v[160:163], v[200:203], v[24:27]
	v_mfma_f32_16x16x32_bf16 v[12:15], v[144:147], v[208:211], v[12:15]
	v_mfma_f32_16x16x32_bf16 v[8:11], v[160:163], v[208:211], v[8:11]
	v_mfma_f32_16x16x32_bf16 v[60:63], v[156:159], v[188:191], v[60:63]
	v_mfma_f32_16x16x32_bf16 v[56:59], v[164:167], v[188:191], v[56:59]
	v_mfma_f32_16x16x32_bf16 v[44:47], v[156:159], v[196:199], v[44:47]
	v_mfma_f32_16x16x32_bf16 v[40:43], v[164:167], v[196:199], v[40:43]
	v_mfma_f32_16x16x32_bf16 v[28:31], v[156:159], v[204:207], v[28:31]
	v_mfma_f32_16x16x32_bf16 v[24:27], v[164:167], v[204:207], v[24:27]
	v_mfma_f32_16x16x32_bf16 v[12:15], v[156:159], v[212:215], v[12:15]
	v_mfma_f32_16x16x32_bf16 v[8:11], v[164:167], v[212:215], v[8:11]
	v_mfma_f32_16x16x32_bf16 v[52:55], v[168:171], v[184:187], v[52:55]
	v_mfma_f32_16x16x32_bf16 v[48:51], v[176:179], v[184:187], v[48:51]
	v_mfma_f32_16x16x32_bf16 v[36:39], v[168:171], v[192:195], v[36:39]
	v_mfma_f32_16x16x32_bf16 v[32:35], v[176:179], v[192:195], v[32:35]
	v_mfma_f32_16x16x32_bf16 v[20:23], v[168:171], v[200:203], v[20:23]
	v_mfma_f32_16x16x32_bf16 v[16:19], v[176:179], v[200:203], v[16:19]
	v_mfma_f32_16x16x32_bf16 v[4:7], v[168:171], v[208:211], v[4:7]
	v_mfma_f32_16x16x32_bf16 v[0:3], v[176:179], v[208:211], v[0:3]
	v_mfma_f32_16x16x32_bf16 v[52:55], v[172:175], v[188:191], v[52:55]
	v_mfma_f32_16x16x32_bf16 v[48:51], v[180:183], v[188:191], v[48:51]
	v_mfma_f32_16x16x32_bf16 v[36:39], v[172:175], v[196:199], v[36:39]
	v_mfma_f32_16x16x32_bf16 v[32:35], v[180:183], v[196:199], v[32:35]
	v_mfma_f32_16x16x32_bf16 v[20:23], v[172:175], v[204:207], v[20:23]
	v_mfma_f32_16x16x32_bf16 v[16:19], v[180:183], v[204:207], v[16:19]
	v_mfma_f32_16x16x32_bf16 v[4:7], v[172:175], v[212:215], v[4:7]
	v_mfma_f32_16x16x32_bf16 v[0:3], v[180:183], v[212:215], v[0:3]
	s_barrier
	s_setprio 0
	s_add_i32 s66, s66, 2
	s_add_u32 s64, s64, 0x100
	s_addc_u32 s65, s65, 0
	s_cmp_gt_u32 s66, 41
	s_mov_b64 s[42:43], s[44:45]
